# v102 + MLA PV phase: the same exps/cvts/prefetch reads re-spaced over the MFMA gaps by issue cost (two S1 exps moved into the first gap; at most 4 exps per gap)
# baseline (speedup 1.0000x reference)
.Lmla_fast_ok_e:
	v_cvt_pk_bf16_f32 v166, v202, v203
	v_cvt_pk_bf16_f32 v167, v204, v205
	v_cvt_pk_bf16_f32 v168, v206, v207
	v_cvt_pk_bf16_f32 v169, v208, v209
	s_waitcnt lgkmcnt(0)
	s_nop 0
	v_mfma_f32_32x32x16_bf16 v[18:33], v[126:129], v[166:169], v[18:33]
	s_add_i32 s8, s30, 1
	s_and_b32 s8, s8, 3
	s_mulk_i32 s8, 0x6400
	v_add3_u32 v0, s8, v143, v132
	v_add3_u32 v142, s8, v144, v145
	v_exp_f32_e32 v218, v34
	v_exp_f32_e32 v219, v35
	v_mfma_f32_32x32x16_bf16 v[2:17], v[122:125], v[166:169], v[2:17]
	v_cvt_pk_bf16_f32 v170, v210, v211
	v_cvt_pk_bf16_f32 v171, v212, v213
	v_cvt_pk_bf16_f32 v172, v214, v215
	v_cvt_pk_bf16_f32 v173, v216, v217
	v_exp_f32_e32 v220, v36
	v_exp_f32_e32 v221, v37
	v_mfma_f32_32x32x16_bf16 v[18:33], v[118:121], v[170:173], v[18:33]
	v_exp_f32_e32 v222, v38
	v_exp_f32_e32 v223, v39
	v_exp_f32_e32 v224, v40
	ds_read_b128 v[194:197], v0
	ds_read_b128 v[150:153], v0 offset:32
	v_mfma_f32_32x32x16_bf16 v[2:17], v[114:117], v[170:173], v[2:17]
	v_exp_f32_e32 v225, v41
	v_cvt_pk_bf16_f32 v166, v218, v219
	v_cvt_pk_bf16_f32 v167, v220, v221
	v_cvt_pk_bf16_f32 v168, v222, v223
	v_cvt_pk_bf16_f32 v169, v224, v225
	ds_read_b128 v[158:161], v0 offset:64
	ds_read_b128 v[162:165], v0 offset:96
	v_mfma_f32_32x32x16_bf16 v[18:33], v[110:113], v[166:169], v[18:33]
	v_exp_f32_e32 v226, v42
	v_exp_f32_e32 v227, v43
	v_exp_f32_e32 v228, v44
	v_exp_f32_e32 v229, v45
	v_mfma_f32_32x32x16_bf16 v[2:17], v[106:109], v[166:169], v[2:17]
	v_exp_f32_e32 v230, v46
	v_exp_f32_e32 v231, v47
	v_exp_f32_e32 v232, v48
	v_exp_f32_e32 v233, v49
	ds_read_b128 v[174:177], v0 offset:128
	ds_read_b128 v[178:181], v0 offset:160
	v_cvt_pk_bf16_f32 v170, v226, v227
	v_cvt_pk_bf16_f32 v171, v228, v229
	v_cvt_pk_bf16_f32 v172, v230, v231
	v_cvt_pk_bf16_f32 v173, v232, v233
	s_add_i32 s30, s30, 1
	s_add_i32 s31, s31, 64
	s_cmp_le_u32 s31, s4
	v_mfma_f32_32x32x16_bf16 v[18:33], v[102:105], v[170:173], v[18:33]
	v_mfma_f32_32x32x16_bf16 v[2:17], v[98:101], v[170:173], v[2:17]
	s_cbranch_scc0 .Lmla_fast_generic

.Lmla_fast_ok_o:
	v_cvt_pk_bf16_f32 v166, v202, v203
	v_cvt_pk_bf16_f32 v167, v204, v205
	v_cvt_pk_bf16_f32 v168, v206, v207
	v_cvt_pk_bf16_f32 v169, v208, v209
	s_waitcnt lgkmcnt(0)
	s_nop 0
	v_mfma_f32_32x32x16_bf16 v[18:33], v[126:129], v[166:169], v[18:33]
	s_add_i32 s8, s30, 1
	s_and_b32 s8, s8, 3
	s_mulk_i32 s8, 0x6400
	v_add3_u32 v0, s8, v143, v132
	v_add3_u32 v142, s8, v144, v145
	v_exp_f32_e32 v218, v34
	v_exp_f32_e32 v219, v35
	v_mfma_f32_32x32x16_bf16 v[2:17], v[122:125], v[166:169], v[2:17]
	v_cvt_pk_bf16_f32 v170, v210, v211
	v_cvt_pk_bf16_f32 v171, v212, v213
	v_cvt_pk_bf16_f32 v172, v214, v215
	v_cvt_pk_bf16_f32 v173, v216, v217
	v_exp_f32_e32 v220, v36
	v_exp_f32_e32 v221, v37
	v_mfma_f32_32x32x16_bf16 v[18:33], v[118:121], v[170:173], v[18:33]
	v_exp_f32_e32 v222, v38
	v_exp_f32_e32 v223, v39
	v_exp_f32_e32 v224, v40
	ds_read_b128 v[194:197], v0
	ds_read_b128 v[150:153], v0 offset:32
	v_mfma_f32_32x32x16_bf16 v[2:17], v[114:117], v[170:173], v[2:17]
	v_exp_f32_e32 v225, v41
	v_cvt_pk_bf16_f32 v166, v218, v219
	v_cvt_pk_bf16_f32 v167, v220, v221
	v_cvt_pk_bf16_f32 v168, v222, v223
	v_cvt_pk_bf16_f32 v169, v224, v225
	ds_read_b128 v[158:161], v0 offset:64
	ds_read_b128 v[162:165], v0 offset:96
	v_mfma_f32_32x32x16_bf16 v[18:33], v[110:113], v[166:169], v[18:33]
	v_exp_f32_e32 v226, v42
	v_exp_f32_e32 v227, v43
	v_exp_f32_e32 v228, v44
	v_exp_f32_e32 v229, v45
	v_mfma_f32_32x32x16_bf16 v[2:17], v[106:109], v[166:169], v[2:17]
	v_exp_f32_e32 v230, v46
	v_exp_f32_e32 v231, v47
	v_exp_f32_e32 v232, v48
	v_exp_f32_e32 v233, v49
	ds_read_b128 v[174:177], v0 offset:128
	ds_read_b128 v[178:181], v0 offset:160
	v_cvt_pk_bf16_f32 v170, v226, v227
	v_cvt_pk_bf16_f32 v171, v228, v229
	v_cvt_pk_bf16_f32 v172, v230, v231
	v_cvt_pk_bf16_f32 v173, v232, v233
	s_add_i32 s30, s30, 1
	s_add_i32 s31, s31, 64
	s_cmp_le_u32 s31, s4
	v_mfma_f32_32x32x16_bf16 v[18:33], v[102:105], v[170:173], v[18:33]
	v_mfma_f32_32x32x16_bf16 v[2:17], v[98:101], v[170:173], v[2:17]
	s_cbranch_scc1 .Lmla_fast_havek_e
	s_branch .Lmla_fast_generic
